# P14 gate+groupnorm phase hand-rewritten as prefetched streaming loop; P11 GEMM k-loop LDS reads rescheduled two k-steps ahead
# speedup vs baseline: 1.0147x; 1.0147x over previous
.LBB0_2250:
	s_or_b64 exec, exec, s[2:3]
	v_add_u32_e32 v4, s27, v180
	v_ashrrev_i32_e32 v5, 31, v4
	v_lshlrev_b64 v[4:5], 11, v[4:5]
	v_lshl_add_u64 v[146:147], s[82:83], 0, v[4:5]
	v_add_u32_e32 v4, s27, v181
	v_ashrrev_i32_e32 v5, 31, v4
	v_lshlrev_b64 v[4:5], 11, v[4:5]
	v_lshl_add_u64 v[154:155], s[82:83], 0, v[4:5]
	v_add_u32_e32 v4, s26, v1
	v_ashrrev_i32_e32 v5, 31, v4
	v_lshlrev_b64 v[4:5], 11, v[4:5]
	v_lshl_add_u64 v[156:157], s[82:83], 0, v[4:5]
	v_add_u32_e32 v4, s27, v1
	v_ashrrev_i32_e32 v5, 31, v4
	v_lshlrev_b64 v[4:5], 11, v[4:5]
	v_lshl_add_u64 v[144:145], s[82:83], 0, v[40:41]
	v_lshl_add_u64 v[148:149], s[82:83], 0, v[38:39]
	v_lshl_add_u64 v[150:151], s[82:83], 0, v[36:37]
	v_lshl_add_u64 v[152:153], s[82:83], 0, v[34:35]
	v_lshl_add_u64 v[158:159], s[82:83], 0, v[4:5]
	s_mov_b32 s13, 0
	v_mov_b32_e32 v3, v2
	v_mov_b32_e32 v4, v2
	v_mov_b32_e32 v5, v2
	v_mov_b32_e32 v6, v2
	v_mov_b32_e32 v7, v2
	v_mov_b32_e32 v8, v2
	v_mov_b32_e32 v9, v2
	v_mov_b32_e32 v10, v2
	v_mov_b32_e32 v11, v2
	v_mov_b32_e32 v12, v2
	v_mov_b32_e32 v13, v2
	v_mov_b32_e32 v14, v2
	v_mov_b32_e32 v15, v2
	v_mov_b32_e32 v16, v2
	v_mov_b32_e32 v17, v2
	v_mov_b32_e32 v18, v2
	v_mov_b32_e32 v19, v2
	v_mov_b32_e32 v20, v2
	v_mov_b32_e32 v21, v2
	v_mov_b32_e32 v22, v2
	v_mov_b32_e32 v23, v2
	v_mov_b32_e32 v24, v2
	v_mov_b32_e32 v25, v2
	v_mov_b32_e32 v26, v2
	v_mov_b32_e32 v27, v2
	v_mov_b32_e32 v28, v2
	v_mov_b32_e32 v29, v2
	v_mov_b32_e32 v30, v2
	v_mov_b32_e32 v31, v2
	v_mov_b32_e32 v32, v2
	v_mov_b32_e32 v33, v2
	v_mov_b32_e32 v34, v2
	v_mov_b32_e32 v35, v2
	v_mov_b32_e32 v36, v2
	v_mov_b32_e32 v37, v2
	v_mov_b32_e32 v38, v2
	v_mov_b32_e32 v39, v2
	v_mov_b32_e32 v40, v2
	v_mov_b32_e32 v41, v2
	v_mov_b32_e32 v42, v2
	v_mov_b32_e32 v43, v2
	v_mov_b32_e32 v44, v2
	v_mov_b32_e32 v45, v2
	v_mov_b32_e32 v46, v2
	v_mov_b32_e32 v47, v2
	v_mov_b32_e32 v48, v2
	v_mov_b32_e32 v49, v2
	v_mov_b32_e32 v50, v2
	v_mov_b32_e32 v51, v2
	v_mov_b32_e32 v52, v2
	v_mov_b32_e32 v53, v2
	v_mov_b32_e32 v54, v2
	v_mov_b32_e32 v55, v2
	v_mov_b32_e32 v56, v2
	v_mov_b32_e32 v57, v2
	v_mov_b32_e32 v58, v2
	v_mov_b32_e32 v59, v2
	v_mov_b32_e32 v60, v2
	v_mov_b32_e32 v61, v2
	v_mov_b32_e32 v62, v2
	v_mov_b32_e32 v63, v2
	v_mov_b32_e32 v64, v2
	v_mov_b32_e32 v65, v2
	s_waitcnt lgkmcnt(0)
	s_barrier
	ds_read_b128 v[212:215], v182 offset:18432
	ds_read_b128 v[216:219], v162 offset:0
	ds_read_b128 v[220:223], v182 offset:23040
	ds_read_b128 v[224:227], v162 offset:4608
	ds_read_b128 v[228:231], v182 offset:18464
	ds_read_b128 v[232:235], v162 offset:32
	ds_read_b128 v[236:239], v182 offset:23072
	ds_read_b128 v[240:243], v162 offset:4640
	s_branch .LBB0_2253

.LBB0_2252:
	s_add_i32 s13, s13, 2
	v_lshl_add_u64 v[144:145], v[144:145], 0, s[22:23]
	v_lshl_add_u64 v[146:147], v[146:147], 0, s[22:23]
	v_lshl_add_u64 v[148:149], v[148:149], 0, s[22:23]
	v_lshl_add_u64 v[150:151], v[150:151], 0, s[22:23]
	v_lshl_add_u64 v[152:153], v[152:153], 0, s[22:23]
	v_lshl_add_u64 v[154:155], v[154:155], 0, s[22:23]
	v_lshl_add_u64 v[156:157], v[156:157], 0, s[22:23]
	v_lshl_add_u64 v[158:159], v[158:159], 0, s[22:23]
	s_andn2_b64 vcc, exec, s[2:3]
	s_waitcnt lgkmcnt(4)
	v_mfma_f32_32x32x16_bf16 v[50:65], v[212:215], v[216:219], v[50:65]
	v_mfma_f32_32x32x16_bf16 v[34:49], v[220:223], v[216:219], v[34:49]
	v_mfma_f32_32x32x16_bf16 v[18:33], v[212:215], v[224:227], v[18:33]
	v_mfma_f32_32x32x16_bf16 v[2:17], v[220:223], v[224:227], v[2:17]
	ds_read_b128 v[184:187], v182 offset:55360
	ds_read_b128 v[188:191], v162 offset:36928
	ds_read_b128 v[192:195], v182 offset:59968
	ds_read_b128 v[196:199], v162 offset:41536
	s_waitcnt lgkmcnt(4)
	v_mfma_f32_32x32x16_bf16 v[50:65], v[228:231], v[232:235], v[50:65]
	v_mfma_f32_32x32x16_bf16 v[34:49], v[236:239], v[232:235], v[34:49]
	v_mfma_f32_32x32x16_bf16 v[18:33], v[228:231], v[240:243], v[18:33]
	v_mfma_f32_32x32x16_bf16 v[2:17], v[236:239], v[240:243], v[2:17]
	ds_read_b128 v[200:203], v182 offset:55392
	ds_read_b128 v[204:207], v162 offset:36960
	ds_read_b128 v[208:211], v182 offset:60000
	ds_read_b128 v[248:251], v162 offset:41568
	s_waitcnt lgkmcnt(4)
	v_mfma_f32_32x32x16_bf16 v[50:65], v[184:187], v[188:191], v[50:65]
	v_mfma_f32_32x32x16_bf16 v[34:49], v[192:195], v[188:191], v[34:49]
	s_waitcnt lgkmcnt(0)
	s_barrier
	ds_read_b128 v[212:215], v182 offset:18432
	ds_read_b128 v[216:219], v162 offset:0
	ds_read_b128 v[220:223], v182 offset:23040
	ds_read_b128 v[224:227], v162 offset:4608
	ds_read_b128 v[228:231], v182 offset:18464
	ds_read_b128 v[232:235], v162 offset:32
	ds_read_b128 v[236:239], v182 offset:23072
	ds_read_b128 v[240:243], v162 offset:4640
	v_mfma_f32_32x32x16_bf16 v[18:33], v[184:187], v[196:199], v[18:33]
	v_mfma_f32_32x32x16_bf16 v[2:17], v[192:195], v[196:199], v[2:17]
	v_mfma_f32_32x32x16_bf16 v[50:65], v[200:203], v[204:207], v[50:65]
	v_mfma_f32_32x32x16_bf16 v[34:49], v[208:211], v[204:207], v[34:49]
	v_mfma_f32_32x32x16_bf16 v[18:33], v[200:203], v[248:251], v[18:33]
	v_mfma_f32_32x32x16_bf16 v[2:17], v[208:211], v[248:251], v[2:17]
	s_cbranch_vccz .LBB0_2265

.LBB0_2259:
	s_cmp_gt_u32 s13, 13
	s_cselect_b64 s[2:3], -1, 0
	s_and_b64 vcc, exec, s[2:3]
	s_waitcnt lgkmcnt(4)
	v_mfma_f32_32x32x16_bf16 v[50:65], v[212:215], v[216:219], v[50:65]
	v_mfma_f32_32x32x16_bf16 v[34:49], v[220:223], v[216:219], v[34:49]
	v_mfma_f32_32x32x16_bf16 v[18:33], v[212:215], v[224:227], v[18:33]
	v_mfma_f32_32x32x16_bf16 v[2:17], v[220:223], v[224:227], v[2:17]
	ds_read_b128 v[184:187], v182 offset:18496
	ds_read_b128 v[188:191], v162 offset:64
	ds_read_b128 v[192:195], v182 offset:23104
	ds_read_b128 v[196:199], v162 offset:4672
	s_waitcnt lgkmcnt(4)
	v_mfma_f32_32x32x16_bf16 v[50:65], v[228:231], v[232:235], v[50:65]
	v_mfma_f32_32x32x16_bf16 v[34:49], v[236:239], v[232:235], v[34:49]
	v_mfma_f32_32x32x16_bf16 v[18:33], v[228:231], v[240:243], v[18:33]
	v_mfma_f32_32x32x16_bf16 v[2:17], v[236:239], v[240:243], v[2:17]
	ds_read_b128 v[200:203], v182 offset:18528
	ds_read_b128 v[204:207], v162 offset:96
	ds_read_b128 v[208:211], v182 offset:23136
	ds_read_b128 v[248:251], v162 offset:4704
	s_waitcnt lgkmcnt(4)
	v_mfma_f32_32x32x16_bf16 v[50:65], v[184:187], v[188:191], v[50:65]
	v_mfma_f32_32x32x16_bf16 v[34:49], v[192:195], v[188:191], v[34:49]
	s_waitcnt lgkmcnt(0)
	s_barrier
	ds_read_b128 v[212:215], v182 offset:55296
	ds_read_b128 v[216:219], v162 offset:36864
	ds_read_b128 v[220:223], v182 offset:59904
	ds_read_b128 v[224:227], v162 offset:41472
	ds_read_b128 v[228:231], v182 offset:55328
	ds_read_b128 v[232:235], v162 offset:36896
	ds_read_b128 v[236:239], v182 offset:59936
	ds_read_b128 v[240:243], v162 offset:41504
	v_mfma_f32_32x32x16_bf16 v[18:33], v[184:187], v[196:199], v[18:33]
	v_mfma_f32_32x32x16_bf16 v[2:17], v[192:195], v[196:199], v[2:17]
	v_mfma_f32_32x32x16_bf16 v[50:65], v[200:203], v[204:207], v[50:65]
	v_mfma_f32_32x32x16_bf16 v[34:49], v[208:211], v[204:207], v[34:49]
	v_mfma_f32_32x32x16_bf16 v[18:33], v[200:203], v[248:251], v[18:33]
	v_mfma_f32_32x32x16_bf16 v[2:17], v[208:211], v[248:251], v[2:17]
	s_cbranch_vccnz .LBB0_2252
	s_cmp_gt_u32 s13, 11
	s_waitcnt vmcnt(5)
	ds_write_b128 v160, v[90:93]
	s_waitcnt vmcnt(4)
	ds_write_b128 v160, v[94:97] offset:18432
	s_waitcnt vmcnt(3)
	ds_write_b128 v160, v[98:101] offset:4608
	s_waitcnt vmcnt(2)
	ds_write_b128 v160, v[106:109] offset:23040
	s_waitcnt vmcnt(1)
	ds_write_b128 v160, v[110:113] offset:9216
	ds_write_b128 v160, v[118:121] offset:27648
	s_waitcnt vmcnt(0)
	ds_write_b128 v160, v[122:125] offset:13824
	ds_write_b128 v160, v[126:129] offset:32256
	s_cbranch_scc1 .LBB0_2252
	v_lshl_add_u64 v[90:91], v[158:159], 0, v[140:141]
	v_add_co_u32_e32 v90, vcc, 0xa380000, v90
	v_lshl_add_u64 v[94:95], v[156:157], 0, v[140:141]
	s_nop 0
	v_addc_co_u32_e32 v91, vcc, 0, v91, vcc
	v_add_co_u32_e32 v94, vcc, 0x8bc0000, v94
	v_lshl_add_u64 v[98:99], v[154:155], 0, v[140:141]
	s_nop 0
	v_addc_co_u32_e32 v95, vcc, 0, v95, vcc
	v_add_co_u32_e32 v98, vcc, 0xa380000, v98
	v_lshl_add_u64 v[106:107], v[152:153], 0, v[140:141]
	s_nop 0
	v_addc_co_u32_e32 v99, vcc, 0, v99, vcc
	v_add_co_u32_e32 v106, vcc, 0x8bc0000, v106
	v_lshl_add_u64 v[110:111], v[150:151], 0, v[140:141]
	s_nop 0
	v_addc_co_u32_e32 v107, vcc, 0, v107, vcc
	v_add_co_u32_e32 v110, vcc, 0xa380000, v110
	global_load_dwordx4 v[90:93], v[90:91], off offset:512
	s_nop 0
	v_addc_co_u32_e32 v111, vcc, 0, v111, vcc
	global_load_dwordx4 v[94:97], v[94:95], off offset:512
	v_mov_b32_e32 v131, v130
	global_load_dwordx4 v[98:101], v[98:99], off offset:512
	v_mov_b64_e32 v[120:121], v[130:131]
	global_load_dwordx4 v[106:109], v[106:107], off offset:512
	v_mov_b64_e32 v[118:119], v[130:131]
	global_load_dwordx4 v[110:113], v[110:111], off offset:512
	s_and_saveexec_b64 s[14:15], s[6:7]
	s_cbranch_execz .LBB0_2263
	v_lshl_add_u64 v[118:119], v[148:149], 0, v[140:141]
	v_add_co_u32_e32 v118, vcc, 0x8bc0000, v118
	s_nop 1
	v_addc_co_u32_e32 v119, vcc, 0, v119, vcc
	global_load_dwordx4 v[118:121], v[118:119], off offset:512

.LBB0_2812:
	v_and_b32_e32 v1, 0x3ff, v0
	v_and_b32_e32 v2, 63, v1
	v_lshlrev_b32_e32 v3, 4, v2
	v_lshlrev_b32_e32 v4, 5, v2
	v_mov_b32_e32 v102, 0x3727c5ac
	v_mov_b32_e32 v97, 0
	v_readfirstlane_b32 s4, v1
	v_readlane_b32 s5, v245, 0
	v_readlane_b32 s6, v245, 9
	s_nop 3
	s_lshr_b32 s4, s4, 6
	s_lshl_b32 s5, s5, 2
	s_add_u32 s5, s5, s4
	s_mov_b32 s19, 0x3b000000
	s_mov_b32 s7, 0x800000
	s_lshl_b32 s14, s6, 2
	s_mov_b32 s17, 0
	s_mov_b32 s15, s5
.Lp14_cnt:
	s_cmp_ge_u32 s15, 68096
	s_cbranch_scc1 .Lp14_cnt_done
	s_add_u32 s17, s17, 1
	s_add_u32 s15, s15, s14
	s_branch .Lp14_cnt
.Lp14_cnt_done:
	s_cmp_eq_u32 s17, 0
	s_cbranch_scc1 .Lp14_end
	s_and_b32 s15, s5, 3
	s_lshr_b32 s18, s5, 2
	s_lshl_b32 s14, s15, 11
	s_add_u32 s0, s68, s14
	s_addc_u32 s1, s69, 0
	global_load_dwordx4 v[8:11], v4, s[0:1]
	global_load_dwordx4 v[12:15], v4, s[0:1] offset:16
	s_lshl_b32 s14, s18, 12
	s_lshr_b32 s23, s18, 20
	s_lshl_b32 s15, s15, 10
	s_add_u32 s14, s14, s15
	s_addc_u32 s23, s23, 0
	s_add_u32 s8, s82, 0x16b00000
	s_addc_u32 s9, s83, 0
	s_add_u32 s8, s8, s14
	s_addc_u32 s9, s9, s23
	s_add_u32 s10, s82, 0xc4c0000
	s_addc_u32 s11, s83, 0
	s_add_u32 s10, s10, s14
	s_addc_u32 s11, s11, s23
	s_add_u32 s12, s82, 0x10740000
	s_addc_u32 s13, s83, 0
	s_add_u32 s12, s12, s14
	s_addc_u32 s13, s13, s23
	s_lshl_b32 s20, s6, 12
	s_lshr_b32 s21, s6, 20
	global_load_dwordx4 v[16:19], v3, s[8:9]
	global_load_dwordx4 v[20:23], v3, s[10:11]
	global_load_dword v48, v3, s[0:1]
	s_add_u32 s18, s18, s6
	s_cmp_lt_u32 s18, 17024
	s_cbranch_scc0 .Lp14_noadv_pro1
	s_add_u32 s8, s8, s20
	s_addc_u32 s9, s9, s21
	s_add_u32 s10, s10, s20
	s_addc_u32 s11, s11, s21
.Lp14_noadv_pro1:
	global_load_dwordx4 v[24:27], v3, s[8:9]
	global_load_dwordx4 v[28:31], v3, s[10:11]
	global_load_dword v48, v3, s[0:1]
	s_add_u32 s18, s18, s6
	s_cmp_lt_u32 s18, 17024
	s_cbranch_scc0 .Lp14_noadv_pro2
	s_add_u32 s8, s8, s20
	s_addc_u32 s9, s9, s21
	s_add_u32 s10, s10, s20
	s_addc_u32 s11, s11, s21
.Lp14_noadv_pro2:
	global_load_dwordx4 v[32:35], v3, s[8:9]
	global_load_dwordx4 v[36:39], v3, s[10:11]
	global_load_dword v48, v3, s[0:1]
	s_mov_b32 s16, 0
.Lp14_loop:
	s_cmp_ge_u32 s16, s17
	s_cbranch_scc1 .Lp14_done
	s_waitcnt vmcnt(7)
	v_lshlrev_b32_e32 v50, 16, v16
	v_and_b32_e32 v51, 0xffff0000, v16
	v_lshlrev_b32_e32 v52, 16, v17
	v_and_b32_e32 v53, 0xffff0000, v17
	v_lshlrev_b32_e32 v54, 16, v18
	v_and_b32_e32 v55, 0xffff0000, v18
	v_lshlrev_b32_e32 v56, 16, v19
	v_and_b32_e32 v57, 0xffff0000, v19
	v_lshlrev_b32_e32 v58, 16, v20
	v_and_b32_e32 v59, 0xffff0000, v20
	v_lshlrev_b32_e32 v60, 16, v21
	v_and_b32_e32 v61, 0xffff0000, v21
	v_lshlrev_b32_e32 v62, 16, v22
	v_and_b32_e32 v63, 0xffff0000, v22
	v_lshlrev_b32_e32 v64, 16, v23
	v_and_b32_e32 v65, 0xffff0000, v23
	s_add_u32 s18, s18, s6
	s_cmp_lt_u32 s18, 17024
	s_cbranch_scc0 .Lp14_noadv_s0
	s_add_u32 s8, s8, s20
	s_addc_u32 s9, s9, s21
	s_add_u32 s10, s10, s20
	s_addc_u32 s11, s11, s21
.Lp14_noadv_s0:
	global_load_dwordx4 v[40:43], v3, s[8:9]
	global_load_dwordx4 v[44:47], v3, s[10:11]
	v_pk_mul_f32 v[50:51], v[50:51], v[58:59]
	v_pk_mul_f32 v[52:53], v[52:53], v[60:61]
	v_pk_mul_f32 v[54:55], v[54:55], v[62:63]
	v_pk_mul_f32 v[56:57], v[56:57], v[64:65]
	v_mul_f32_e32 v66, 0xbfb8aa3b, v58
	v_mul_f32_e32 v67, 0xbfb8aa3b, v59
	v_mul_f32_e32 v68, 0xbfb8aa3b, v60
	v_mul_f32_e32 v69, 0xbfb8aa3b, v61
	v_mul_f32_e32 v70, 0xbfb8aa3b, v62
	v_mul_f32_e32 v71, 0xbfb8aa3b, v63
	v_mul_f32_e32 v72, 0xbfb8aa3b, v64
	v_mul_f32_e32 v73, 0xbfb8aa3b, v65
	v_exp_f32_e32 v66, v66
	v_exp_f32_e32 v67, v67
	v_exp_f32_e32 v68, v68
	v_exp_f32_e32 v69, v69
	v_exp_f32_e32 v70, v70
	v_exp_f32_e32 v71, v71
	v_exp_f32_e32 v72, v72
	v_exp_f32_e32 v73, v73
	s_nop 0
	v_pk_add_f32 v[66:67], v[66:67], 1.0 op_sel_hi:[1,0]
	v_pk_add_f32 v[68:69], v[68:69], 1.0 op_sel_hi:[1,0]
	v_pk_add_f32 v[70:71], v[70:71], 1.0 op_sel_hi:[1,0]
	v_pk_add_f32 v[72:73], v[72:73], 1.0 op_sel_hi:[1,0]
	v_div_scale_f32 v74, s[22:23], v66, v66, 1.0
	v_rcp_f32_e32 v75, v74
	v_div_scale_f32 v76, vcc, 1.0, v66, 1.0
	v_fma_f32 v77, -v74, v75, 1.0
	v_fmac_f32_e32 v75, v77, v75
	v_mul_f32_e32 v78, v76, v75
	v_fma_f32 v77, -v74, v78, v76
	v_fmac_f32_e32 v78, v77, v75
	v_fma_f32 v77, -v74, v78, v76
	v_div_fmas_f32 v79, v77, v75, v78
	v_div_fixup_f32 v66, v79, v66, 1.0
	v_div_scale_f32 v74, s[22:23], v67, v67, 1.0
	v_rcp_f32_e32 v75, v74
	v_div_scale_f32 v76, vcc, 1.0, v67, 1.0
	v_fma_f32 v77, -v74, v75, 1.0
	v_fmac_f32_e32 v75, v77, v75
	v_mul_f32_e32 v78, v76, v75
	v_fma_f32 v77, -v74, v78, v76
	v_fmac_f32_e32 v78, v77, v75
	v_fma_f32 v77, -v74, v78, v76
	v_div_fmas_f32 v79, v77, v75, v78
	v_div_fixup_f32 v67, v79, v67, 1.0
	v_div_scale_f32 v74, s[22:23], v68, v68, 1.0
	v_rcp_f32_e32 v75, v74
	v_div_scale_f32 v76, vcc, 1.0, v68, 1.0
	v_fma_f32 v77, -v74, v75, 1.0
	v_fmac_f32_e32 v75, v77, v75
	v_mul_f32_e32 v78, v76, v75
	v_fma_f32 v77, -v74, v78, v76
	v_fmac_f32_e32 v78, v77, v75
	v_fma_f32 v77, -v74, v78, v76
	v_div_fmas_f32 v79, v77, v75, v78
	v_div_fixup_f32 v68, v79, v68, 1.0
	v_div_scale_f32 v74, s[22:23], v69, v69, 1.0
	v_rcp_f32_e32 v75, v74
	v_div_scale_f32 v76, vcc, 1.0, v69, 1.0
	v_fma_f32 v77, -v74, v75, 1.0
	v_fmac_f32_e32 v75, v77, v75
	v_mul_f32_e32 v78, v76, v75
	v_fma_f32 v77, -v74, v78, v76
	v_fmac_f32_e32 v78, v77, v75
	v_fma_f32 v77, -v74, v78, v76
	v_div_fmas_f32 v79, v77, v75, v78
	v_div_fixup_f32 v69, v79, v69, 1.0
	v_div_scale_f32 v74, s[22:23], v70, v70, 1.0
	v_rcp_f32_e32 v75, v74
	v_div_scale_f32 v76, vcc, 1.0, v70, 1.0
	v_fma_f32 v77, -v74, v75, 1.0
	v_fmac_f32_e32 v75, v77, v75
	v_mul_f32_e32 v78, v76, v75
	v_fma_f32 v77, -v74, v78, v76
	v_fmac_f32_e32 v78, v77, v75
	v_fma_f32 v77, -v74, v78, v76
	v_div_fmas_f32 v79, v77, v75, v78
	v_div_fixup_f32 v70, v79, v70, 1.0
	v_div_scale_f32 v74, s[22:23], v71, v71, 1.0
	v_rcp_f32_e32 v75, v74
	v_div_scale_f32 v76, vcc, 1.0, v71, 1.0
	v_fma_f32 v77, -v74, v75, 1.0
	v_fmac_f32_e32 v75, v77, v75
	v_mul_f32_e32 v78, v76, v75
	v_fma_f32 v77, -v74, v78, v76
	v_fmac_f32_e32 v78, v77, v75
	v_fma_f32 v77, -v74, v78, v76
	v_div_fmas_f32 v79, v77, v75, v78
	v_div_fixup_f32 v71, v79, v71, 1.0
	v_div_scale_f32 v74, s[22:23], v72, v72, 1.0
	v_rcp_f32_e32 v75, v74
	v_div_scale_f32 v76, vcc, 1.0, v72, 1.0
	v_fma_f32 v77, -v74, v75, 1.0
	v_fmac_f32_e32 v75, v77, v75
	v_mul_f32_e32 v78, v76, v75
	v_fma_f32 v77, -v74, v78, v76
	v_fmac_f32_e32 v78, v77, v75
	v_fma_f32 v77, -v74, v78, v76
	v_div_fmas_f32 v79, v77, v75, v78
	v_div_fixup_f32 v72, v79, v72, 1.0
	v_div_scale_f32 v74, s[22:23], v73, v73, 1.0
	v_rcp_f32_e32 v75, v74
	v_div_scale_f32 v76, vcc, 1.0, v73, 1.0
	v_fma_f32 v77, -v74, v75, 1.0
	v_fmac_f32_e32 v75, v77, v75
	v_mul_f32_e32 v78, v76, v75
	v_fma_f32 v77, -v74, v78, v76
	v_fmac_f32_e32 v78, v77, v75
	v_fma_f32 v77, -v74, v78, v76
	v_div_fmas_f32 v79, v77, v75, v78
	v_div_fixup_f32 v73, v79, v73, 1.0
	v_pk_mul_f32 v[50:51], v[50:51], v[66:67]
	v_pk_mul_f32 v[52:53], v[52:53], v[68:69]
	v_pk_mul_f32 v[54:55], v[54:55], v[70:71]
	v_pk_mul_f32 v[56:57], v[56:57], v[72:73]
	v_pk_mul_f32 v[80:81], v[50:51], v[50:51]
	v_pk_mul_f32 v[82:83], v[52:53], v[52:53]
	v_pk_mul_f32 v[84:85], v[54:55], v[54:55]
	v_pk_mul_f32 v[86:87], v[56:57], v[56:57]
	v_add_f32_e32 v88, v80, v81
	v_add_f32_e32 v88, v88, v82
	v_add_f32_e32 v88, v83, v88
	v_add_f32_e32 v88, v84, v88
	v_add_f32_e32 v88, v85, v88
	v_add_f32_e32 v88, v86, v88
	v_add_f32_e32 v88, v87, v88
	s_nop 1
	v_add_f32_dpp v88, v88, v88 quad_perm:[1,0,3,2] row_mask:0xf bank_mask:0xf bound_ctrl:1
	s_nop 1
	v_add_f32_dpp v88, v88, v88 quad_perm:[2,3,0,1] row_mask:0xf bank_mask:0xf bound_ctrl:1
	s_nop 1
	v_add_f32_dpp v88, v88, v88 row_half_mirror row_mask:0xf bank_mask:0xf bound_ctrl:1
	s_nop 1
	v_add_f32_dpp v88, v88, v88 row_mirror row_mask:0xf bank_mask:0xf bound_ctrl:1
	s_nop 1
	v_readlane_b32 s4, v88, 16
	v_readlane_b32 s5, v88, 48
	v_readlane_b32 s0, v88, 0
	v_readlane_b32 s1, v88, 32
	v_mov_b32_e32 v89, s4
	v_mov_b32_e32 v90, s5
	s_nop 0
	v_add_f32_e32 v89, s0, v89
	v_add_f32_e32 v90, s1, v90
	v_add_f32_e32 v89, v89, v90
	v_fma_f32 v91, v89, s19, v102
	v_mul_f32_e32 v92, 0x4b800000, v91
	v_cmp_gt_f32_e32 vcc, s7, v91
	s_nop 1
	v_cndmask_b32_e32 v92, v91, v92, vcc
	v_rsq_f32_e32 v93, v92
	s_nop 0
	v_mul_f32_e32 v94, 0x45800000, v93
	v_cndmask_b32_e32 v96, v93, v94, vcc
	v_pk_mul_f32 v[50:51], v[50:51], v[96:97] op_sel_hi:[1,0]
	v_pk_mul_f32 v[52:53], v[52:53], v[96:97] op_sel_hi:[1,0]
	v_pk_mul_f32 v[54:55], v[54:55], v[96:97] op_sel_hi:[1,0]
	v_pk_mul_f32 v[56:57], v[56:57], v[96:97] op_sel_hi:[1,0]
	v_pk_mul_f32 v[50:51], v[8:9], v[50:51]
	v_pk_mul_f32 v[52:53], v[10:11], v[52:53]
	v_pk_mul_f32 v[54:55], v[12:13], v[54:55]
	v_pk_mul_f32 v[56:57], v[14:15], v[56:57]
	v_cvt_pk_bf16_f32 v98, v50, v51
	v_cvt_pk_bf16_f32 v99, v52, v53
	v_cvt_pk_bf16_f32 v100, v54, v55
	v_cvt_pk_bf16_f32 v101, v56, v57
	global_store_dwordx4 v3, v[98:101], s[12:13]
	s_add_u32 s12, s12, s20
	s_addc_u32 s13, s13, s21
	s_add_u32 s16, s16, 1
	s_cmp_ge_u32 s16, s17
	s_cbranch_scc1 .Lp14_done
	s_waitcnt vmcnt(7)
	v_lshlrev_b32_e32 v50, 16, v24
	v_and_b32_e32 v51, 0xffff0000, v24
	v_lshlrev_b32_e32 v52, 16, v25
	v_and_b32_e32 v53, 0xffff0000, v25
	v_lshlrev_b32_e32 v54, 16, v26
	v_and_b32_e32 v55, 0xffff0000, v26
	v_lshlrev_b32_e32 v56, 16, v27
	v_and_b32_e32 v57, 0xffff0000, v27
	v_lshlrev_b32_e32 v58, 16, v28
	v_and_b32_e32 v59, 0xffff0000, v28
	v_lshlrev_b32_e32 v60, 16, v29
	v_and_b32_e32 v61, 0xffff0000, v29
	v_lshlrev_b32_e32 v62, 16, v30
	v_and_b32_e32 v63, 0xffff0000, v30
	v_lshlrev_b32_e32 v64, 16, v31
	v_and_b32_e32 v65, 0xffff0000, v31
	s_add_u32 s18, s18, s6
	s_cmp_lt_u32 s18, 17024
	s_cbranch_scc0 .Lp14_noadv_s1
	s_add_u32 s8, s8, s20
	s_addc_u32 s9, s9, s21
	s_add_u32 s10, s10, s20
	s_addc_u32 s11, s11, s21
.Lp14_noadv_s1:
	global_load_dwordx4 v[16:19], v3, s[8:9]
	global_load_dwordx4 v[20:23], v3, s[10:11]
	v_pk_mul_f32 v[50:51], v[50:51], v[58:59]
	v_pk_mul_f32 v[52:53], v[52:53], v[60:61]
	v_pk_mul_f32 v[54:55], v[54:55], v[62:63]
	v_pk_mul_f32 v[56:57], v[56:57], v[64:65]
	v_mul_f32_e32 v66, 0xbfb8aa3b, v58
	v_mul_f32_e32 v67, 0xbfb8aa3b, v59
	v_mul_f32_e32 v68, 0xbfb8aa3b, v60
	v_mul_f32_e32 v69, 0xbfb8aa3b, v61
	v_mul_f32_e32 v70, 0xbfb8aa3b, v62
	v_mul_f32_e32 v71, 0xbfb8aa3b, v63
	v_mul_f32_e32 v72, 0xbfb8aa3b, v64
	v_mul_f32_e32 v73, 0xbfb8aa3b, v65
	v_exp_f32_e32 v66, v66
	v_exp_f32_e32 v67, v67
	v_exp_f32_e32 v68, v68
	v_exp_f32_e32 v69, v69
	v_exp_f32_e32 v70, v70
	v_exp_f32_e32 v71, v71
	v_exp_f32_e32 v72, v72
	v_exp_f32_e32 v73, v73
	s_nop 0
	v_pk_add_f32 v[66:67], v[66:67], 1.0 op_sel_hi:[1,0]
	v_pk_add_f32 v[68:69], v[68:69], 1.0 op_sel_hi:[1,0]
	v_pk_add_f32 v[70:71], v[70:71], 1.0 op_sel_hi:[1,0]
	v_pk_add_f32 v[72:73], v[72:73], 1.0 op_sel_hi:[1,0]
	v_div_scale_f32 v74, s[22:23], v66, v66, 1.0
	v_rcp_f32_e32 v75, v74
	v_div_scale_f32 v76, vcc, 1.0, v66, 1.0
	v_fma_f32 v77, -v74, v75, 1.0
	v_fmac_f32_e32 v75, v77, v75
	v_mul_f32_e32 v78, v76, v75
	v_fma_f32 v77, -v74, v78, v76
	v_fmac_f32_e32 v78, v77, v75
	v_fma_f32 v77, -v74, v78, v76
	v_div_fmas_f32 v79, v77, v75, v78
	v_div_fixup_f32 v66, v79, v66, 1.0
	v_div_scale_f32 v74, s[22:23], v67, v67, 1.0
	v_rcp_f32_e32 v75, v74
	v_div_scale_f32 v76, vcc, 1.0, v67, 1.0
	v_fma_f32 v77, -v74, v75, 1.0
	v_fmac_f32_e32 v75, v77, v75
	v_mul_f32_e32 v78, v76, v75
	v_fma_f32 v77, -v74, v78, v76
	v_fmac_f32_e32 v78, v77, v75
	v_fma_f32 v77, -v74, v78, v76
	v_div_fmas_f32 v79, v77, v75, v78
	v_div_fixup_f32 v67, v79, v67, 1.0
	v_div_scale_f32 v74, s[22:23], v68, v68, 1.0
	v_rcp_f32_e32 v75, v74
	v_div_scale_f32 v76, vcc, 1.0, v68, 1.0
	v_fma_f32 v77, -v74, v75, 1.0
	v_fmac_f32_e32 v75, v77, v75
	v_mul_f32_e32 v78, v76, v75
	v_fma_f32 v77, -v74, v78, v76
	v_fmac_f32_e32 v78, v77, v75
	v_fma_f32 v77, -v74, v78, v76
	v_div_fmas_f32 v79, v77, v75, v78
	v_div_fixup_f32 v68, v79, v68, 1.0
	v_div_scale_f32 v74, s[22:23], v69, v69, 1.0
	v_rcp_f32_e32 v75, v74
	v_div_scale_f32 v76, vcc, 1.0, v69, 1.0
	v_fma_f32 v77, -v74, v75, 1.0
	v_fmac_f32_e32 v75, v77, v75
	v_mul_f32_e32 v78, v76, v75
	v_fma_f32 v77, -v74, v78, v76
	v_fmac_f32_e32 v78, v77, v75
	v_fma_f32 v77, -v74, v78, v76
	v_div_fmas_f32 v79, v77, v75, v78
	v_div_fixup_f32 v69, v79, v69, 1.0
	v_div_scale_f32 v74, s[22:23], v70, v70, 1.0
	v_rcp_f32_e32 v75, v74
	v_div_scale_f32 v76, vcc, 1.0, v70, 1.0
	v_fma_f32 v77, -v74, v75, 1.0
	v_fmac_f32_e32 v75, v77, v75
	v_mul_f32_e32 v78, v76, v75
	v_fma_f32 v77, -v74, v78, v76
	v_fmac_f32_e32 v78, v77, v75
	v_fma_f32 v77, -v74, v78, v76
	v_div_fmas_f32 v79, v77, v75, v78
	v_div_fixup_f32 v70, v79, v70, 1.0
	v_div_scale_f32 v74, s[22:23], v71, v71, 1.0
	v_rcp_f32_e32 v75, v74
	v_div_scale_f32 v76, vcc, 1.0, v71, 1.0
	v_fma_f32 v77, -v74, v75, 1.0
	v_fmac_f32_e32 v75, v77, v75
	v_mul_f32_e32 v78, v76, v75
	v_fma_f32 v77, -v74, v78, v76
	v_fmac_f32_e32 v78, v77, v75
	v_fma_f32 v77, -v74, v78, v76
	v_div_fmas_f32 v79, v77, v75, v78
	v_div_fixup_f32 v71, v79, v71, 1.0
	v_div_scale_f32 v74, s[22:23], v72, v72, 1.0
	v_rcp_f32_e32 v75, v74
	v_div_scale_f32 v76, vcc, 1.0, v72, 1.0
	v_fma_f32 v77, -v74, v75, 1.0
	v_fmac_f32_e32 v75, v77, v75
	v_mul_f32_e32 v78, v76, v75
	v_fma_f32 v77, -v74, v78, v76
	v_fmac_f32_e32 v78, v77, v75
	v_fma_f32 v77, -v74, v78, v76
	v_div_fmas_f32 v79, v77, v75, v78
	v_div_fixup_f32 v72, v79, v72, 1.0
	v_div_scale_f32 v74, s[22:23], v73, v73, 1.0
	v_rcp_f32_e32 v75, v74
	v_div_scale_f32 v76, vcc, 1.0, v73, 1.0
	v_fma_f32 v77, -v74, v75, 1.0
	v_fmac_f32_e32 v75, v77, v75
	v_mul_f32_e32 v78, v76, v75
	v_fma_f32 v77, -v74, v78, v76
	v_fmac_f32_e32 v78, v77, v75
	v_fma_f32 v77, -v74, v78, v76
	v_div_fmas_f32 v79, v77, v75, v78
	v_div_fixup_f32 v73, v79, v73, 1.0
	v_pk_mul_f32 v[50:51], v[50:51], v[66:67]
	v_pk_mul_f32 v[52:53], v[52:53], v[68:69]
	v_pk_mul_f32 v[54:55], v[54:55], v[70:71]
	v_pk_mul_f32 v[56:57], v[56:57], v[72:73]
	v_pk_mul_f32 v[80:81], v[50:51], v[50:51]
	v_pk_mul_f32 v[82:83], v[52:53], v[52:53]
	v_pk_mul_f32 v[84:85], v[54:55], v[54:55]
	v_pk_mul_f32 v[86:87], v[56:57], v[56:57]
	v_add_f32_e32 v88, v80, v81
	v_add_f32_e32 v88, v88, v82
	v_add_f32_e32 v88, v83, v88
	v_add_f32_e32 v88, v84, v88
	v_add_f32_e32 v88, v85, v88
	v_add_f32_e32 v88, v86, v88
	v_add_f32_e32 v88, v87, v88
	s_nop 1
	v_add_f32_dpp v88, v88, v88 quad_perm:[1,0,3,2] row_mask:0xf bank_mask:0xf bound_ctrl:1
	s_nop 1
	v_add_f32_dpp v88, v88, v88 quad_perm:[2,3,0,1] row_mask:0xf bank_mask:0xf bound_ctrl:1
	s_nop 1
	v_add_f32_dpp v88, v88, v88 row_half_mirror row_mask:0xf bank_mask:0xf bound_ctrl:1
	s_nop 1
	v_add_f32_dpp v88, v88, v88 row_mirror row_mask:0xf bank_mask:0xf bound_ctrl:1
	s_nop 1
	v_readlane_b32 s4, v88, 16
	v_readlane_b32 s5, v88, 48
	v_readlane_b32 s0, v88, 0
	v_readlane_b32 s1, v88, 32
	v_mov_b32_e32 v89, s4
	v_mov_b32_e32 v90, s5
	s_nop 0
	v_add_f32_e32 v89, s0, v89
	v_add_f32_e32 v90, s1, v90
	v_add_f32_e32 v89, v89, v90
	v_fma_f32 v91, v89, s19, v102
	v_mul_f32_e32 v92, 0x4b800000, v91
	v_cmp_gt_f32_e32 vcc, s7, v91
	s_nop 1
	v_cndmask_b32_e32 v92, v91, v92, vcc
	v_rsq_f32_e32 v93, v92
	s_nop 0
	v_mul_f32_e32 v94, 0x45800000, v93
	v_cndmask_b32_e32 v96, v93, v94, vcc
	v_pk_mul_f32 v[50:51], v[50:51], v[96:97] op_sel_hi:[1,0]
	v_pk_mul_f32 v[52:53], v[52:53], v[96:97] op_sel_hi:[1,0]
	v_pk_mul_f32 v[54:55], v[54:55], v[96:97] op_sel_hi:[1,0]
	v_pk_mul_f32 v[56:57], v[56:57], v[96:97] op_sel_hi:[1,0]
	v_pk_mul_f32 v[50:51], v[8:9], v[50:51]
	v_pk_mul_f32 v[52:53], v[10:11], v[52:53]
	v_pk_mul_f32 v[54:55], v[12:13], v[54:55]
	v_pk_mul_f32 v[56:57], v[14:15], v[56:57]
	v_cvt_pk_bf16_f32 v98, v50, v51
	v_cvt_pk_bf16_f32 v99, v52, v53
	v_cvt_pk_bf16_f32 v100, v54, v55
	v_cvt_pk_bf16_f32 v101, v56, v57
	global_store_dwordx4 v3, v[98:101], s[12:13]
	s_add_u32 s12, s12, s20
	s_addc_u32 s13, s13, s21
	s_add_u32 s16, s16, 1
	s_cmp_ge_u32 s16, s17
	s_cbranch_scc1 .Lp14_done
	s_waitcnt vmcnt(7)
	v_lshlrev_b32_e32 v50, 16, v32
	v_and_b32_e32 v51, 0xffff0000, v32
	v_lshlrev_b32_e32 v52, 16, v33
	v_and_b32_e32 v53, 0xffff0000, v33
	v_lshlrev_b32_e32 v54, 16, v34
	v_and_b32_e32 v55, 0xffff0000, v34
	v_lshlrev_b32_e32 v56, 16, v35
	v_and_b32_e32 v57, 0xffff0000, v35
	v_lshlrev_b32_e32 v58, 16, v36
	v_and_b32_e32 v59, 0xffff0000, v36
	v_lshlrev_b32_e32 v60, 16, v37
	v_and_b32_e32 v61, 0xffff0000, v37
	v_lshlrev_b32_e32 v62, 16, v38
	v_and_b32_e32 v63, 0xffff0000, v38
	v_lshlrev_b32_e32 v64, 16, v39
	v_and_b32_e32 v65, 0xffff0000, v39
	s_add_u32 s18, s18, s6
	s_cmp_lt_u32 s18, 17024
	s_cbranch_scc0 .Lp14_noadv_s2
	s_add_u32 s8, s8, s20
	s_addc_u32 s9, s9, s21
	s_add_u32 s10, s10, s20
	s_addc_u32 s11, s11, s21
.Lp14_noadv_s2:
	global_load_dwordx4 v[24:27], v3, s[8:9]
	global_load_dwordx4 v[28:31], v3, s[10:11]
	v_pk_mul_f32 v[50:51], v[50:51], v[58:59]
	v_pk_mul_f32 v[52:53], v[52:53], v[60:61]
	v_pk_mul_f32 v[54:55], v[54:55], v[62:63]
	v_pk_mul_f32 v[56:57], v[56:57], v[64:65]
	v_mul_f32_e32 v66, 0xbfb8aa3b, v58
	v_mul_f32_e32 v67, 0xbfb8aa3b, v59
	v_mul_f32_e32 v68, 0xbfb8aa3b, v60
	v_mul_f32_e32 v69, 0xbfb8aa3b, v61
	v_mul_f32_e32 v70, 0xbfb8aa3b, v62
	v_mul_f32_e32 v71, 0xbfb8aa3b, v63
	v_mul_f32_e32 v72, 0xbfb8aa3b, v64
	v_mul_f32_e32 v73, 0xbfb8aa3b, v65
	v_exp_f32_e32 v66, v66
	v_exp_f32_e32 v67, v67
	v_exp_f32_e32 v68, v68
	v_exp_f32_e32 v69, v69
	v_exp_f32_e32 v70, v70
	v_exp_f32_e32 v71, v71
	v_exp_f32_e32 v72, v72
	v_exp_f32_e32 v73, v73
	s_nop 0
	v_pk_add_f32 v[66:67], v[66:67], 1.0 op_sel_hi:[1,0]
	v_pk_add_f32 v[68:69], v[68:69], 1.0 op_sel_hi:[1,0]
	v_pk_add_f32 v[70:71], v[70:71], 1.0 op_sel_hi:[1,0]
	v_pk_add_f32 v[72:73], v[72:73], 1.0 op_sel_hi:[1,0]
	v_div_scale_f32 v74, s[22:23], v66, v66, 1.0
	v_rcp_f32_e32 v75, v74
	v_div_scale_f32 v76, vcc, 1.0, v66, 1.0
	v_fma_f32 v77, -v74, v75, 1.0
	v_fmac_f32_e32 v75, v77, v75
	v_mul_f32_e32 v78, v76, v75
	v_fma_f32 v77, -v74, v78, v76
	v_fmac_f32_e32 v78, v77, v75
	v_fma_f32 v77, -v74, v78, v76
	v_div_fmas_f32 v79, v77, v75, v78
	v_div_fixup_f32 v66, v79, v66, 1.0
	v_div_scale_f32 v74, s[22:23], v67, v67, 1.0
	v_rcp_f32_e32 v75, v74
	v_div_scale_f32 v76, vcc, 1.0, v67, 1.0
	v_fma_f32 v77, -v74, v75, 1.0
	v_fmac_f32_e32 v75, v77, v75
	v_mul_f32_e32 v78, v76, v75
	v_fma_f32 v77, -v74, v78, v76
	v_fmac_f32_e32 v78, v77, v75
	v_fma_f32 v77, -v74, v78, v76
	v_div_fmas_f32 v79, v77, v75, v78
	v_div_fixup_f32 v67, v79, v67, 1.0
	v_div_scale_f32 v74, s[22:23], v68, v68, 1.0
	v_rcp_f32_e32 v75, v74
	v_div_scale_f32 v76, vcc, 1.0, v68, 1.0
	v_fma_f32 v77, -v74, v75, 1.0
	v_fmac_f32_e32 v75, v77, v75
	v_mul_f32_e32 v78, v76, v75
	v_fma_f32 v77, -v74, v78, v76
	v_fmac_f32_e32 v78, v77, v75
	v_fma_f32 v77, -v74, v78, v76
	v_div_fmas_f32 v79, v77, v75, v78
	v_div_fixup_f32 v68, v79, v68, 1.0
	v_div_scale_f32 v74, s[22:23], v69, v69, 1.0
	v_rcp_f32_e32 v75, v74
	v_div_scale_f32 v76, vcc, 1.0, v69, 1.0
	v_fma_f32 v77, -v74, v75, 1.0
	v_fmac_f32_e32 v75, v77, v75
	v_mul_f32_e32 v78, v76, v75
	v_fma_f32 v77, -v74, v78, v76
	v_fmac_f32_e32 v78, v77, v75
	v_fma_f32 v77, -v74, v78, v76
	v_div_fmas_f32 v79, v77, v75, v78
	v_div_fixup_f32 v69, v79, v69, 1.0
	v_div_scale_f32 v74, s[22:23], v70, v70, 1.0
	v_rcp_f32_e32 v75, v74
	v_div_scale_f32 v76, vcc, 1.0, v70, 1.0
	v_fma_f32 v77, -v74, v75, 1.0
	v_fmac_f32_e32 v75, v77, v75
	v_mul_f32_e32 v78, v76, v75
	v_fma_f32 v77, -v74, v78, v76
	v_fmac_f32_e32 v78, v77, v75
	v_fma_f32 v77, -v74, v78, v76
	v_div_fmas_f32 v79, v77, v75, v78
	v_div_fixup_f32 v70, v79, v70, 1.0
	v_div_scale_f32 v74, s[22:23], v71, v71, 1.0
	v_rcp_f32_e32 v75, v74
	v_div_scale_f32 v76, vcc, 1.0, v71, 1.0
	v_fma_f32 v77, -v74, v75, 1.0
	v_fmac_f32_e32 v75, v77, v75
	v_mul_f32_e32 v78, v76, v75
	v_fma_f32 v77, -v74, v78, v76
	v_fmac_f32_e32 v78, v77, v75
	v_fma_f32 v77, -v74, v78, v76
	v_div_fmas_f32 v79, v77, v75, v78
	v_div_fixup_f32 v71, v79, v71, 1.0
	v_div_scale_f32 v74, s[22:23], v72, v72, 1.0
	v_rcp_f32_e32 v75, v74
	v_div_scale_f32 v76, vcc, 1.0, v72, 1.0
	v_fma_f32 v77, -v74, v75, 1.0
	v_fmac_f32_e32 v75, v77, v75
	v_mul_f32_e32 v78, v76, v75
	v_fma_f32 v77, -v74, v78, v76
	v_fmac_f32_e32 v78, v77, v75
	v_fma_f32 v77, -v74, v78, v76
	v_div_fmas_f32 v79, v77, v75, v78
	v_div_fixup_f32 v72, v79, v72, 1.0
	v_div_scale_f32 v74, s[22:23], v73, v73, 1.0
	v_rcp_f32_e32 v75, v74
	v_div_scale_f32 v76, vcc, 1.0, v73, 1.0
	v_fma_f32 v77, -v74, v75, 1.0
	v_fmac_f32_e32 v75, v77, v75
	v_mul_f32_e32 v78, v76, v75
	v_fma_f32 v77, -v74, v78, v76
	v_fmac_f32_e32 v78, v77, v75
	v_fma_f32 v77, -v74, v78, v76
	v_div_fmas_f32 v79, v77, v75, v78
	v_div_fixup_f32 v73, v79, v73, 1.0
	v_pk_mul_f32 v[50:51], v[50:51], v[66:67]
	v_pk_mul_f32 v[52:53], v[52:53], v[68:69]
	v_pk_mul_f32 v[54:55], v[54:55], v[70:71]
	v_pk_mul_f32 v[56:57], v[56:57], v[72:73]
	v_pk_mul_f32 v[80:81], v[50:51], v[50:51]
	v_pk_mul_f32 v[82:83], v[52:53], v[52:53]
	v_pk_mul_f32 v[84:85], v[54:55], v[54:55]
	v_pk_mul_f32 v[86:87], v[56:57], v[56:57]
	v_add_f32_e32 v88, v80, v81
	v_add_f32_e32 v88, v88, v82
	v_add_f32_e32 v88, v83, v88
	v_add_f32_e32 v88, v84, v88
	v_add_f32_e32 v88, v85, v88
	v_add_f32_e32 v88, v86, v88
	v_add_f32_e32 v88, v87, v88
	s_nop 1
	v_add_f32_dpp v88, v88, v88 quad_perm:[1,0,3,2] row_mask:0xf bank_mask:0xf bound_ctrl:1
	s_nop 1
	v_add_f32_dpp v88, v88, v88 quad_perm:[2,3,0,1] row_mask:0xf bank_mask:0xf bound_ctrl:1
	s_nop 1
	v_add_f32_dpp v88, v88, v88 row_half_mirror row_mask:0xf bank_mask:0xf bound_ctrl:1
	s_nop 1
	v_add_f32_dpp v88, v88, v88 row_mirror row_mask:0xf bank_mask:0xf bound_ctrl:1
	s_nop 1
	v_readlane_b32 s4, v88, 16
	v_readlane_b32 s5, v88, 48
	v_readlane_b32 s0, v88, 0
	v_readlane_b32 s1, v88, 32
	v_mov_b32_e32 v89, s4
	v_mov_b32_e32 v90, s5
	s_nop 0
	v_add_f32_e32 v89, s0, v89
	v_add_f32_e32 v90, s1, v90
	v_add_f32_e32 v89, v89, v90
	v_fma_f32 v91, v89, s19, v102
	v_mul_f32_e32 v92, 0x4b800000, v91
	v_cmp_gt_f32_e32 vcc, s7, v91
	s_nop 1
	v_cndmask_b32_e32 v92, v91, v92, vcc
	v_rsq_f32_e32 v93, v92
	s_nop 0
	v_mul_f32_e32 v94, 0x45800000, v93
	v_cndmask_b32_e32 v96, v93, v94, vcc
	v_pk_mul_f32 v[50:51], v[50:51], v[96:97] op_sel_hi:[1,0]
	v_pk_mul_f32 v[52:53], v[52:53], v[96:97] op_sel_hi:[1,0]
	v_pk_mul_f32 v[54:55], v[54:55], v[96:97] op_sel_hi:[1,0]
	v_pk_mul_f32 v[56:57], v[56:57], v[96:97] op_sel_hi:[1,0]
	v_pk_mul_f32 v[50:51], v[8:9], v[50:51]
	v_pk_mul_f32 v[52:53], v[10:11], v[52:53]
	v_pk_mul_f32 v[54:55], v[12:13], v[54:55]
	v_pk_mul_f32 v[56:57], v[14:15], v[56:57]
	v_cvt_pk_bf16_f32 v98, v50, v51
	v_cvt_pk_bf16_f32 v99, v52, v53
	v_cvt_pk_bf16_f32 v100, v54, v55
	v_cvt_pk_bf16_f32 v101, v56, v57
	global_store_dwordx4 v3, v[98:101], s[12:13]
	s_add_u32 s12, s12, s20
	s_addc_u32 s13, s13, s21
	s_add_u32 s16, s16, 1
	s_cmp_ge_u32 s16, s17
	s_cbranch_scc1 .Lp14_done
	s_waitcnt vmcnt(7)
	v_lshlrev_b32_e32 v50, 16, v40
	v_and_b32_e32 v51, 0xffff0000, v40
	v_lshlrev_b32_e32 v52, 16, v41
	v_and_b32_e32 v53, 0xffff0000, v41
	v_lshlrev_b32_e32 v54, 16, v42
	v_and_b32_e32 v55, 0xffff0000, v42
	v_lshlrev_b32_e32 v56, 16, v43
	v_and_b32_e32 v57, 0xffff0000, v43
	v_lshlrev_b32_e32 v58, 16, v44
	v_and_b32_e32 v59, 0xffff0000, v44
	v_lshlrev_b32_e32 v60, 16, v45
	v_and_b32_e32 v61, 0xffff0000, v45
	v_lshlrev_b32_e32 v62, 16, v46
	v_and_b32_e32 v63, 0xffff0000, v46
	v_lshlrev_b32_e32 v64, 16, v47
	v_and_b32_e32 v65, 0xffff0000, v47
	s_add_u32 s18, s18, s6
	s_cmp_lt_u32 s18, 17024
	s_cbranch_scc0 .Lp14_noadv_s3
	s_add_u32 s8, s8, s20
	s_addc_u32 s9, s9, s21
	s_add_u32 s10, s10, s20
	s_addc_u32 s11, s11, s21
.Lp14_noadv_s3:
	global_load_dwordx4 v[32:35], v3, s[8:9]
	global_load_dwordx4 v[36:39], v3, s[10:11]
	v_pk_mul_f32 v[50:51], v[50:51], v[58:59]
	v_pk_mul_f32 v[52:53], v[52:53], v[60:61]
	v_pk_mul_f32 v[54:55], v[54:55], v[62:63]
	v_pk_mul_f32 v[56:57], v[56:57], v[64:65]
	v_mul_f32_e32 v66, 0xbfb8aa3b, v58
	v_mul_f32_e32 v67, 0xbfb8aa3b, v59
	v_mul_f32_e32 v68, 0xbfb8aa3b, v60
	v_mul_f32_e32 v69, 0xbfb8aa3b, v61
	v_mul_f32_e32 v70, 0xbfb8aa3b, v62
	v_mul_f32_e32 v71, 0xbfb8aa3b, v63
	v_mul_f32_e32 v72, 0xbfb8aa3b, v64
	v_mul_f32_e32 v73, 0xbfb8aa3b, v65
	v_exp_f32_e32 v66, v66
	v_exp_f32_e32 v67, v67
	v_exp_f32_e32 v68, v68
	v_exp_f32_e32 v69, v69
	v_exp_f32_e32 v70, v70
	v_exp_f32_e32 v71, v71
	v_exp_f32_e32 v72, v72
	v_exp_f32_e32 v73, v73
	s_nop 0
	v_pk_add_f32 v[66:67], v[66:67], 1.0 op_sel_hi:[1,0]
	v_pk_add_f32 v[68:69], v[68:69], 1.0 op_sel_hi:[1,0]
	v_pk_add_f32 v[70:71], v[70:71], 1.0 op_sel_hi:[1,0]
	v_pk_add_f32 v[72:73], v[72:73], 1.0 op_sel_hi:[1,0]
	v_div_scale_f32 v74, s[22:23], v66, v66, 1.0
	v_rcp_f32_e32 v75, v74
	v_div_scale_f32 v76, vcc, 1.0, v66, 1.0
	v_fma_f32 v77, -v74, v75, 1.0
	v_fmac_f32_e32 v75, v77, v75
	v_mul_f32_e32 v78, v76, v75
	v_fma_f32 v77, -v74, v78, v76
	v_fmac_f32_e32 v78, v77, v75
	v_fma_f32 v77, -v74, v78, v76
	v_div_fmas_f32 v79, v77, v75, v78
	v_div_fixup_f32 v66, v79, v66, 1.0
	v_div_scale_f32 v74, s[22:23], v67, v67, 1.0
	v_rcp_f32_e32 v75, v74
	v_div_scale_f32 v76, vcc, 1.0, v67, 1.0
	v_fma_f32 v77, -v74, v75, 1.0
	v_fmac_f32_e32 v75, v77, v75
	v_mul_f32_e32 v78, v76, v75
	v_fma_f32 v77, -v74, v78, v76
	v_fmac_f32_e32 v78, v77, v75
	v_fma_f32 v77, -v74, v78, v76
	v_div_fmas_f32 v79, v77, v75, v78
	v_div_fixup_f32 v67, v79, v67, 1.0
	v_div_scale_f32 v74, s[22:23], v68, v68, 1.0
	v_rcp_f32_e32 v75, v74
	v_div_scale_f32 v76, vcc, 1.0, v68, 1.0
	v_fma_f32 v77, -v74, v75, 1.0
	v_fmac_f32_e32 v75, v77, v75
	v_mul_f32_e32 v78, v76, v75
	v_fma_f32 v77, -v74, v78, v76
	v_fmac_f32_e32 v78, v77, v75
	v_fma_f32 v77, -v74, v78, v76
	v_div_fmas_f32 v79, v77, v75, v78
	v_div_fixup_f32 v68, v79, v68, 1.0
	v_div_scale_f32 v74, s[22:23], v69, v69, 1.0
	v_rcp_f32_e32 v75, v74
	v_div_scale_f32 v76, vcc, 1.0, v69, 1.0
	v_fma_f32 v77, -v74, v75, 1.0
	v_fmac_f32_e32 v75, v77, v75
	v_mul_f32_e32 v78, v76, v75
	v_fma_f32 v77, -v74, v78, v76
	v_fmac_f32_e32 v78, v77, v75
	v_fma_f32 v77, -v74, v78, v76
	v_div_fmas_f32 v79, v77, v75, v78
	v_div_fixup_f32 v69, v79, v69, 1.0
	v_div_scale_f32 v74, s[22:23], v70, v70, 1.0
	v_rcp_f32_e32 v75, v74
	v_div_scale_f32 v76, vcc, 1.0, v70, 1.0
	v_fma_f32 v77, -v74, v75, 1.0
	v_fmac_f32_e32 v75, v77, v75
	v_mul_f32_e32 v78, v76, v75
	v_fma_f32 v77, -v74, v78, v76
	v_fmac_f32_e32 v78, v77, v75
	v_fma_f32 v77, -v74, v78, v76
	v_div_fmas_f32 v79, v77, v75, v78
	v_div_fixup_f32 v70, v79, v70, 1.0
	v_div_scale_f32 v74, s[22:23], v71, v71, 1.0
	v_rcp_f32_e32 v75, v74
	v_div_scale_f32 v76, vcc, 1.0, v71, 1.0
	v_fma_f32 v77, -v74, v75, 1.0
	v_fmac_f32_e32 v75, v77, v75
	v_mul_f32_e32 v78, v76, v75
	v_fma_f32 v77, -v74, v78, v76
	v_fmac_f32_e32 v78, v77, v75
	v_fma_f32 v77, -v74, v78, v76
	v_div_fmas_f32 v79, v77, v75, v78
	v_div_fixup_f32 v71, v79, v71, 1.0
	v_div_scale_f32 v74, s[22:23], v72, v72, 1.0
	v_rcp_f32_e32 v75, v74
	v_div_scale_f32 v76, vcc, 1.0, v72, 1.0
	v_fma_f32 v77, -v74, v75, 1.0
	v_fmac_f32_e32 v75, v77, v75
	v_mul_f32_e32 v78, v76, v75
	v_fma_f32 v77, -v74, v78, v76
	v_fmac_f32_e32 v78, v77, v75
	v_fma_f32 v77, -v74, v78, v76
	v_div_fmas_f32 v79, v77, v75, v78
	v_div_fixup_f32 v72, v79, v72, 1.0
	v_div_scale_f32 v74, s[22:23], v73, v73, 1.0
	v_rcp_f32_e32 v75, v74
	v_div_scale_f32 v76, vcc, 1.0, v73, 1.0
	v_fma_f32 v77, -v74, v75, 1.0
	v_fmac_f32_e32 v75, v77, v75
	v_mul_f32_e32 v78, v76, v75
	v_fma_f32 v77, -v74, v78, v76
	v_fmac_f32_e32 v78, v77, v75
	v_fma_f32 v77, -v74, v78, v76
	v_div_fmas_f32 v79, v77, v75, v78
	v_div_fixup_f32 v73, v79, v73, 1.0
	v_pk_mul_f32 v[50:51], v[50:51], v[66:67]
	v_pk_mul_f32 v[52:53], v[52:53], v[68:69]
	v_pk_mul_f32 v[54:55], v[54:55], v[70:71]
	v_pk_mul_f32 v[56:57], v[56:57], v[72:73]
	v_pk_mul_f32 v[80:81], v[50:51], v[50:51]
	v_pk_mul_f32 v[82:83], v[52:53], v[52:53]
	v_pk_mul_f32 v[84:85], v[54:55], v[54:55]
	v_pk_mul_f32 v[86:87], v[56:57], v[56:57]
	v_add_f32_e32 v88, v80, v81
	v_add_f32_e32 v88, v88, v82
	v_add_f32_e32 v88, v83, v88
	v_add_f32_e32 v88, v84, v88
	v_add_f32_e32 v88, v85, v88
	v_add_f32_e32 v88, v86, v88
	v_add_f32_e32 v88, v87, v88
	s_nop 1
	v_add_f32_dpp v88, v88, v88 quad_perm:[1,0,3,2] row_mask:0xf bank_mask:0xf bound_ctrl:1
	s_nop 1
	v_add_f32_dpp v88, v88, v88 quad_perm:[2,3,0,1] row_mask:0xf bank_mask:0xf bound_ctrl:1
	s_nop 1
	v_add_f32_dpp v88, v88, v88 row_half_mirror row_mask:0xf bank_mask:0xf bound_ctrl:1
	s_nop 1
	v_add_f32_dpp v88, v88, v88 row_mirror row_mask:0xf bank_mask:0xf bound_ctrl:1
	s_nop 1
	v_readlane_b32 s4, v88, 16
	v_readlane_b32 s5, v88, 48
	v_readlane_b32 s0, v88, 0
	v_readlane_b32 s1, v88, 32
	v_mov_b32_e32 v89, s4
	v_mov_b32_e32 v90, s5
	s_nop 0
	v_add_f32_e32 v89, s0, v89
	v_add_f32_e32 v90, s1, v90
	v_add_f32_e32 v89, v89, v90
	v_fma_f32 v91, v89, s19, v102
	v_mul_f32_e32 v92, 0x4b800000, v91
	v_cmp_gt_f32_e32 vcc, s7, v91
	s_nop 1
	v_cndmask_b32_e32 v92, v91, v92, vcc
	v_rsq_f32_e32 v93, v92
	s_nop 0
	v_mul_f32_e32 v94, 0x45800000, v93
	v_cndmask_b32_e32 v96, v93, v94, vcc
	v_pk_mul_f32 v[50:51], v[50:51], v[96:97] op_sel_hi:[1,0]
	v_pk_mul_f32 v[52:53], v[52:53], v[96:97] op_sel_hi:[1,0]
	v_pk_mul_f32 v[54:55], v[54:55], v[96:97] op_sel_hi:[1,0]
	v_pk_mul_f32 v[56:57], v[56:57], v[96:97] op_sel_hi:[1,0]
	v_pk_mul_f32 v[50:51], v[8:9], v[50:51]
	v_pk_mul_f32 v[52:53], v[10:11], v[52:53]
	v_pk_mul_f32 v[54:55], v[12:13], v[54:55]
	v_pk_mul_f32 v[56:57], v[14:15], v[56:57]
	v_cvt_pk_bf16_f32 v98, v50, v51
	v_cvt_pk_bf16_f32 v99, v52, v53
	v_cvt_pk_bf16_f32 v100, v54, v55
	v_cvt_pk_bf16_f32 v101, v56, v57
	global_store_dwordx4 v3, v[98:101], s[12:13]
	s_add_u32 s12, s12, s20
	s_addc_u32 s13, s13, s21
	s_add_u32 s16, s16, 1
	s_branch .Lp14_loop

.Lp14_end:
.LBB0_2816:
	v_readlane_b32 s4, v245, 7
	v_readlane_b32 s5, v245, 8
	s_cmp_gt_i32 s4, 15
	s_cselect_b64 s[12:13], -1, 0
	s_cmp_lt_i32 s5, 16
	s_cselect_b64 s[0:1], -1, 0
	s_or_b64 s[0:1], s[12:13], s[0:1]
	s_and_b64 vcc, exec, s[0:1]
	v_readlane_b32 s6, v245, 9
	v_readlane_b32 s7, v245, 10
	s_cbranch_vccnz .LBB0_2945
	s_andn2_b64 vcc, exec, s[2:3]
	s_cbranch_vccnz .LBB0_2819
	v_and_b32_e32 v4, 0x3ff, v0
	s_cbranch_execz .LBB0_2820
	s_branch .LBB0_2882

	.amdhsa_kernel _Z14fwd_megakernel6Params
		.amdhsa_group_segment_fixed_size 73744
		.amdhsa_private_segment_fixed_size 0
		.amdhsa_kernarg_size 584
		.amdhsa_user_sgpr_count 2
		.amdhsa_user_sgpr_dispatch_ptr 0
		.amdhsa_user_sgpr_queue_ptr 0
		.amdhsa_user_sgpr_kernarg_segment_ptr 1
		.amdhsa_user_sgpr_dispatch_id 0
		.amdhsa_user_sgpr_kernarg_preload_length 0
		.amdhsa_user_sgpr_kernarg_preload_offset 0
		.amdhsa_user_sgpr_private_segment_size 0
		.amdhsa_uses_dynamic_stack 0
		.amdhsa_enable_private_segment 0
		.amdhsa_system_sgpr_workgroup_id_x 1
		.amdhsa_system_sgpr_workgroup_id_y 0
		.amdhsa_system_sgpr_workgroup_id_z 0
		.amdhsa_system_sgpr_workgroup_info 0
		.amdhsa_system_vgpr_workitem_id 2
		.amdhsa_next_free_vgpr 256
		.amdhsa_next_free_sgpr 98
		.amdhsa_accum_offset 256
		.amdhsa_reserve_vcc 1
		.amdhsa_float_round_mode_32 0
		.amdhsa_float_round_mode_16_64 0
		.amdhsa_float_denorm_mode_32 3
		.amdhsa_float_denorm_mode_16_64 3
		.amdhsa_dx10_clamp 1
		.amdhsa_ieee_mode 1
		.amdhsa_fp16_overflow 0
		.amdhsa_tg_split 0
		.amdhsa_exception_fp_ieee_invalid_op 0
		.amdhsa_exception_fp_denorm_src 0
		.amdhsa_exception_fp_ieee_div_zero 0
		.amdhsa_exception_fp_ieee_overflow 0
		.amdhsa_exception_fp_ieee_underflow 0
		.amdhsa_exception_fp_ieee_inexact 0
		.amdhsa_exception_int_div_zero 0
	.end_amdhsa_kernel

amdhsa.kernels:
  - .agpr_count:     0
    .args:
      - .offset:         0
        .size:           328
        .value_kind:     by_value
      - .offset:         328
        .size:           4
        .value_kind:     hidden_block_count_x
      - .offset:         332
        .size:           4
        .value_kind:     hidden_block_count_y
      - .offset:         336
        .size:           4
        .value_kind:     hidden_block_count_z
      - .offset:         340
        .size:           2
        .value_kind:     hidden_group_size_x
      - .offset:         342
        .size:           2
        .value_kind:     hidden_group_size_y
      - .offset:         344
        .size:           2
        .value_kind:     hidden_group_size_z
      - .offset:         346
        .size:           2
        .value_kind:     hidden_remainder_x
      - .offset:         348
        .size:           2
        .value_kind:     hidden_remainder_y
      - .offset:         350
        .size:           2
        .value_kind:     hidden_remainder_z
      - .offset:         368
        .size:           8
        .value_kind:     hidden_global_offset_x
      - .offset:         376
        .size:           8
        .value_kind:     hidden_global_offset_y
      - .offset:         384
        .size:           8
        .value_kind:     hidden_global_offset_z
      - .offset:         392
        .size:           2
        .value_kind:     hidden_grid_dims
      - .offset:         416
        .size:           8
        .value_kind:     hidden_multigrid_sync_arg
    .group_segment_fixed_size: 73744
    .kernarg_segment_align: 8
    .kernarg_segment_size: 584
    .language:       OpenCL C
    .language_version:
      - 2
      - 0
    .max_flat_workgroup_size: 256
    .name:           _Z14fwd_megakernel6Params
    .private_segment_fixed_size: 0
    .sgpr_count:     104
    .sgpr_spill_count: 127
    .symbol:         _Z14fwd_megakernel6Params.kd
    .uniform_work_group_size: 1
    .uses_dynamic_stack: false
    .vgpr_count:     256
    .vgpr_spill_count: 0
    .wavefront_size: 64
